# final stag P.V after the tile loop: read/wait/MFMA ladder replaced by 8-deep LDS fragment ring
# baseline (speedup 1.0000x reference)
.LBB0_383:
	s_mul_hi_i32 s18, s11, 0x55555556
	s_lshr_b32 s19, s18, 31
	s_add_i32 s18, s18, s19
	s_mul_i32 s18, s18, 3
	s_sub_i32 s11, s11, s18
	s_lshl_b32 s11, s11, 14
	s_setprio 1
	s_add_i32 s11, s11, 0
	v_add_u32_e32 v208, s11, v185
	ds_read_b128 v[220:223], v208 offset:32768
	ds_read_b128 v[224:227], v208 offset:33792
	ds_read_b128 v[228:231], v208 offset:34816
	ds_read_b128 v[232:235], v208 offset:35840
	ds_read_b128 v[236:239], v208 offset:36864
	ds_read_b128 v[240:243], v208 offset:37888
	ds_read_b128 v[244:247], v208 offset:38912
	ds_read_b128 v[248:251], v208 offset:39936
	s_waitcnt lgkmcnt(7)
	v_mfma_f32_16x16x32_bf16 v[64:67], v[220:223], v[122:125], v[64:67]
	v_mfma_f32_16x16x32_bf16 v[60:63], v[220:223], v[130:133], v[60:63]
	ds_read_b128 v[220:223], v208 offset:40960
	s_waitcnt lgkmcnt(7)
	v_mfma_f32_16x16x32_bf16 v[64:67], v[224:227], v[118:121], v[64:67]
	v_mfma_f32_16x16x32_bf16 v[60:63], v[224:227], v[126:129], v[60:63]
	ds_read_b128 v[224:227], v208 offset:41984
	s_waitcnt lgkmcnt(7)
	v_mfma_f32_16x16x32_bf16 v[56:59], v[228:231], v[122:125], v[56:59]
	v_mfma_f32_16x16x32_bf16 v[52:55], v[228:231], v[130:133], v[52:55]
	ds_read_b128 v[228:231], v208 offset:43008
	s_waitcnt lgkmcnt(7)
	v_mfma_f32_16x16x32_bf16 v[56:59], v[232:235], v[118:121], v[56:59]
	v_mfma_f32_16x16x32_bf16 v[52:55], v[232:235], v[126:129], v[52:55]
	ds_read_b128 v[232:235], v208 offset:44032
	s_waitcnt lgkmcnt(7)
	v_mfma_f32_16x16x32_bf16 v[48:51], v[236:239], v[122:125], v[48:51]
	v_mfma_f32_16x16x32_bf16 v[44:47], v[236:239], v[130:133], v[44:47]
	ds_read_b128 v[236:239], v208 offset:45056
	s_waitcnt lgkmcnt(7)
	v_mfma_f32_16x16x32_bf16 v[48:51], v[240:243], v[118:121], v[48:51]
	v_mfma_f32_16x16x32_bf16 v[44:47], v[240:243], v[126:129], v[44:47]
	ds_read_b128 v[240:243], v208 offset:46080
	s_waitcnt lgkmcnt(7)
	v_mfma_f32_16x16x32_bf16 v[40:43], v[244:247], v[122:125], v[40:43]
	v_mfma_f32_16x16x32_bf16 v[36:39], v[244:247], v[130:133], v[36:39]
	ds_read_b128 v[244:247], v208 offset:47104
	s_waitcnt lgkmcnt(7)
	v_mfma_f32_16x16x32_bf16 v[40:43], v[248:251], v[118:121], v[40:43]
	v_mfma_f32_16x16x32_bf16 v[36:39], v[248:251], v[126:129], v[36:39]
	ds_read_b128 v[248:251], v208 offset:48128
	s_waitcnt lgkmcnt(7)
	v_mfma_f32_16x16x32_bf16 v[32:35], v[220:223], v[122:125], v[32:35]
	v_mfma_f32_16x16x32_bf16 v[28:31], v[220:223], v[130:133], v[28:31]
	s_waitcnt lgkmcnt(6)
	v_mfma_f32_16x16x32_bf16 v[32:35], v[224:227], v[118:121], v[32:35]
	v_mfma_f32_16x16x32_bf16 v[28:31], v[224:227], v[126:129], v[28:31]
	s_waitcnt lgkmcnt(5)
	v_mfma_f32_16x16x32_bf16 v[24:27], v[228:231], v[122:125], v[24:27]
	v_mfma_f32_16x16x32_bf16 v[20:23], v[228:231], v[130:133], v[20:23]
	s_waitcnt lgkmcnt(4)
	v_mfma_f32_16x16x32_bf16 v[24:27], v[232:235], v[118:121], v[24:27]
	v_mfma_f32_16x16x32_bf16 v[20:23], v[232:235], v[126:129], v[20:23]
	s_waitcnt lgkmcnt(3)
	v_mfma_f32_16x16x32_bf16 v[16:19], v[236:239], v[122:125], v[16:19]
	v_mfma_f32_16x16x32_bf16 v[12:15], v[236:239], v[130:133], v[12:15]
	s_waitcnt lgkmcnt(2)
	v_mfma_f32_16x16x32_bf16 v[16:19], v[240:243], v[118:121], v[16:19]
	v_mfma_f32_16x16x32_bf16 v[12:15], v[240:243], v[126:129], v[12:15]
	s_waitcnt lgkmcnt(1)
	v_mfma_f32_16x16x32_bf16 v[72:75], v[244:247], v[122:125], v[72:75]
	v_mfma_f32_16x16x32_bf16 v[68:71], v[244:247], v[130:133], v[68:71]
	s_waitcnt lgkmcnt(0)
	v_mfma_f32_16x16x32_bf16 v[72:75], v[248:251], v[118:121], v[72:75]
	v_mfma_f32_16x16x32_bf16 v[68:71], v[248:251], v[126:129], v[68:71]
	s_setprio 0
